# attention loop: K/V prefetch addresses as running pointers, zero-fill of skipped-half P operands off the common path
# speedup vs baseline: 1.0153x; 1.0049x over previous
; #define SLOAD(KT) do { _Pragma("unroll") for (int ii = 0; ii < 4; ++ii) { const u16* kp = kbase + (size_t)((KT) * 64 + sr + 16 * ii) * 3072; \
;       stk[ii] = *(const u32x4*)kp; stv[ii] = *(const u32x4*)(kp + 1024); } } while (0)
; #define SWRITE(B) do { _Pragma("unroll") for (int ii = 0; ii < 4; ++ii) { const int row = sr + 16 * ii; \
;       *(u32x4*)(K_lds0 + (B) * 32768 + KSWZ(row, sc * 2)) = stk[ii]; *(u32x4*)(V_lds0 + (B) * 32768 + v_st(row, sc)) = stv[ii]; } } while (0)
; __device__ __forceinline__ void attn_phase(const Params& p, char* smem, int bid, int nblk) {
;     ...
;     const int j = 63 - (i >> 5), bh = i & 31, b = bh >> 3, h = bh & 7;
;     const int i0 = j * 128;
;     const size_t rowb = (size_t)b * SEQ;
;     const int t = i0 + wid * 32 + r32, tmin = i0 + wid * 32, tmax = tmin + 31;
;     bf16x8 qr[8];
;     {
;       const u16* qp = qkv + (rowb + t) * 3072 + h * 128 + hi * 8;
; #pragma unroll
;       for (int d0 = 0; d0 < 8; ++d0) qr[d0] = *(const bf16x8*)(qp + d0 * 16);
;     }
;     f32x16 o[4];
; #pragma unroll
;     for (int d = 0; d < 4; ++d)
; #pragma unroll
;       for (int r = 0; r < 16; ++r) o[d][r] = 0.f;
;     float run = 1.f;
;     const u16* kbase = qkv + rowb * 3072 + 1024 + h * 128 + sc;
;     u32x4 stk[4], stv[4];
;     ...
;     const int NT = 2 * j + 2;
;     __syncthreads();
;     SLOAD(NT - 1); SWRITE(0); __syncthreads();
;     ...
;           pa2 = bf16x8{0, 0, 0, 0, 0, 0, 0, 0}; pa3 = pa2;
.LBB0_1786:
	s_ashr_i32 s7, s6, 5
	s_sub_i32 s0, 63, s7
	s_waitcnt lgkmcnt(0)
	s_lshl_b32 s8, s0, 7
	v_add_u32_e32 v230, s8, v190
	s_lshl_b32 s0, s6, 10
	v_or_b32_e32 v174, v230, v188
	s_and_b32 s38, s0, 0x6000
	v_ashrrev_i32_e32 v175, 31, v174
	v_lshl_add_u64 v[0:1], v[174:175], 0, s[38:39]
	v_mov_b64_e32 v[2:3], s[36:37]
	v_mad_u64_u32 v[2:3], s[0:1], v0, s3, v[2:3]
	s_lshl_b32 s0, s6, 7
	s_and_b32 s52, s0, 0x380
	v_mad_i32_i24 v3, v1, s3, v3
	s_lshl_b32 s0, s52, 1
	s_mov_b32 s1, s39
	v_lshl_add_u64 v[0:1], v[2:3], 0, s[0:1]
	s_mul_i32 s1, s38, 0x1800
	s_add_u32 s1, s36, s1
	s_addc_u32 s6, s37, 0
	s_add_u32 s0, s1, s0
	s_addc_u32 s1, s6, 0
	v_mov_b32_e32 v173, v153
	v_lshl_add_u64 v[0:1], v[0:1], 0, v[152:153]
	v_lshl_add_u64 v[176:177], s[0:1], 0, v[172:173]
	v_add_u32_e32 v4, s8, v191
	global_load_dwordx4 v[80:83], v[0:1], off
	global_load_dwordx4 v[84:87], v[0:1], off offset:32
	global_load_dwordx4 v[88:91], v[0:1], off offset:64
	global_load_dwordx4 v[92:95], v[0:1], off offset:96
	global_load_dwordx4 v[96:99], v[0:1], off offset:128
	global_load_dwordx4 v[100:103], v[0:1], off offset:160
	global_load_dwordx4 v[104:107], v[0:1], off offset:192
	global_load_dwordx4 v[108:111], v[0:1], off offset:224
	v_mad_i64_i32 v[0:1], s[0:1], v4, s3, v[176:177]
	v_lshl_add_u64 v[246:247], v[0:1], 0, s[40:41]
	s_barrier
	v_lshl_add_u64 v[2:3], v[0:1], 0, s[40:41]
	global_load_dwordx4 v[112:115], v[0:1], off offset:2048
	global_load_dwordx4 v[116:119], v[2:3], off offset:2048
	v_add_u32_e32 v0, 16, v4
	v_mad_i64_i32 v[0:1], s[0:1], v0, s3, v[176:177]
	v_lshl_add_u64 v[248:249], v[0:1], 0, s[40:41]
	v_lshl_add_u64 v[2:3], v[0:1], 0, s[40:41]
	global_load_dwordx4 v[120:123], v[0:1], off offset:2048
	global_load_dwordx4 v[124:127], v[2:3], off offset:2048
	v_add_u32_e32 v0, 32, v4
	v_mad_i64_i32 v[0:1], s[0:1], v0, s3, v[176:177]
	v_lshl_add_u64 v[250:251], v[0:1], 0, s[40:41]
	v_lshl_add_u64 v[2:3], v[0:1], 0, s[40:41]
	global_load_dwordx4 v[128:131], v[0:1], off offset:2048
	global_load_dwordx4 v[132:135], v[2:3], off offset:2048
	v_add_u32_e32 v0, 48, v4
	v_mad_i64_i32 v[0:1], s[0:1], v0, s3, v[176:177]
	v_lshl_add_u64 v[252:253], v[0:1], 0, s[40:41]
	v_lshl_add_u64 v[2:3], v[0:1], 0, s[40:41]
	global_load_dwordx4 v[136:139], v[0:1], off offset:2048
	global_load_dwordx4 v[140:143], v[2:3], off offset:2048
	v_mov_b32_e32 v14, v153
	v_mov_b32_e32 v15, v153
	v_mov_b32_e32 v0, v153
	v_mov_b32_e32 v1, v153
	v_mov_b32_e32 v2, v153
	v_mov_b32_e32 v3, v153
	v_mov_b32_e32 v4, v153
	v_mov_b32_e32 v5, v153
	v_mov_b32_e32 v6, v153
	v_mov_b32_e32 v7, v153
	v_mov_b32_e32 v8, v153
	v_mov_b32_e32 v9, v153
	v_mov_b32_e32 v10, v153
	v_mov_b32_e32 v11, v153
	v_mov_b32_e32 v12, v153
	v_mov_b32_e32 v13, v153
	s_lshl_b32 s0, s7, 1
	s_lshl_b32 s1, s7, 7
	v_mov_b64_e32 v[30:31], v[14:15]
	v_mov_b64_e32 v[46:47], v[14:15]
	v_mov_b64_e32 v[62:63], v[14:15]
	s_mov_b32 s53, 0
	v_or_b32_e32 v173, 31, v230
	s_sub_i32 s54, 0x80, s0
	s_sub_i32 s55, 0x1fff, s1
	v_mov_b32_e32 v179, 1.0
	v_mov_b64_e32 v[28:29], v[12:13]
	v_mov_b64_e32 v[26:27], v[10:11]
	v_mov_b64_e32 v[24:25], v[8:9]
	v_mov_b64_e32 v[22:23], v[6:7]
	v_mov_b64_e32 v[20:21], v[4:5]
	v_mov_b64_e32 v[18:19], v[2:3]
	v_mov_b64_e32 v[16:17], v[0:1]
	v_mov_b64_e32 v[44:45], v[12:13]
	v_mov_b64_e32 v[42:43], v[10:11]
	v_mov_b64_e32 v[40:41], v[8:9]
	v_mov_b64_e32 v[38:39], v[6:7]
	v_mov_b64_e32 v[36:37], v[4:5]
	v_mov_b64_e32 v[34:35], v[2:3]
	v_mov_b64_e32 v[32:33], v[0:1]
	v_mov_b64_e32 v[60:61], v[12:13]
	v_mov_b64_e32 v[58:59], v[10:11]
	v_mov_b64_e32 v[56:57], v[8:9]
	v_mov_b64_e32 v[54:55], v[6:7]
	v_mov_b64_e32 v[52:53], v[4:5]
	v_mov_b64_e32 v[50:51], v[2:3]
	v_mov_b64_e32 v[48:49], v[0:1]
	s_waitcnt vmcnt(7)
	ds_write_b128 v222, v[112:115]
	s_waitcnt vmcnt(6)
	ds_write_b128 v223, v[116:119] offset:16384
	s_waitcnt vmcnt(5)
	ds_write_b128 v224, v[120:123]
	s_waitcnt vmcnt(4)
	ds_write_b128 v225, v[124:127] offset:16384
	s_waitcnt vmcnt(3)
	ds_write_b128 v226, v[128:131]
	s_waitcnt vmcnt(2)
	ds_write_b128 v227, v[132:135] offset:16384
	s_waitcnt vmcnt(1)
	ds_write_b128 v228, v[136:139]
	s_waitcnt vmcnt(0)
	ds_write_b128 v229, v[140:143] offset:16384
	s_waitcnt lgkmcnt(0)
	s_barrier
	s_branch .LBB0_1788
.Lattn_zero:
	s_or_b64 exec, exec, s[48:49]
	v_mov_b32_e32 v144, 0
	v_mov_b32_e32 v145, 0
	v_mov_b32_e32 v146, 0
	v_mov_b32_e32 v147, 0
	v_mov_b32_e32 v148, 0
	v_mov_b32_e32 v149, 0
	v_mov_b32_e32 v150, 0
	v_mov_b32_e32 v151, 0
	s_branch .LBB0_1797

; #define SLOAD(KT) do { _Pragma("unroll") for (int ii = 0; ii < 4; ++ii) { const u16* kp = kbase + (size_t)((KT) * 64 + sr + 16 * ii) * 3072; \
;       stk[ii] = *(const u32x4*)kp; stv[ii] = *(const u32x4*)(kp + 1024); } } while (0)
; #define SWRITE(B) do { _Pragma("unroll") for (int ii = 0; ii < 4; ++ii) { const int row = sr + 16 * ii; \
;       *(u32x4*)(K_lds0 + (B) * 32768 + KSWZ(row, sc * 2)) = stk[ii]; *(u32x4*)(V_lds0 + (B) * 32768 + v_st(row, sc)) = stv[ii]; } } while (0)
; __device__ __forceinline__ void sb_half(f32x16& pz, float& run, bool need_mask, int kb, int t, int hi) {
;     ...
; #pragma unroll
;   for (int r = 0; r < 16; ++r) {
;     const float e = __builtin_amdgcn_exp2f(fminf(pz[r] * C2, 60.f));
;     l[r] = __builtin_amdgcn_rcpf(1.f + e);
;     pz[r] = e;
;   }
; __device__ __forceinline__ void attn_phase(const Params& p, char* smem, int bid, int nblk) {
;     ...
;     const int NT = 2 * j + 2;
;     __syncthreads();
;     SLOAD(NT - 1); SWRITE(0); __syncthreads();
;     int cur = 0;
;     ...
;       const int k0 = kt * 64;
;       const char* K_lds = K_lds0 + cur * 32768; const int vb0 = vb00 + cur * 32768;
;       if (kt > 0) SLOAD(kt - 1);
;       if (k0 <= tmax) {
;         bf16x8 pa0, pa1, pa2, pa3;
;     ...
;         if (k0 + 32 <= tmax) {
;           f32x16 pz;
; #pragma unroll
;           for (int r = 0; r < 16; ++r) pz[r] = 0.f;
; #pragma unroll
;           for (int d0 = 0; d0 < 8; ++d0) {
;             const bf16x8 kf = *(const bf16x8*)(K_lds + KSWZ(32 + r32, (d0 * 16 + hi * 8) * 2));
;             pz = __builtin_amdgcn_mfma_f32_32x32x16_bf16(kf, qr[d0], pz, 0, 0, 0);
;           }
;           sb_half(pz, run, k0 + 63 >= tmin, k0 + 32, t, hi);
.LBB0_1788:
	s_cmp_lg_u32 s54, 1
	s_cselect_b64 s[42:43], -1, 0
	s_cmp_eq_u32 s54, 1
	s_cbranch_scc1 .LBB0_1790
	s_mov_b32 s98, 0xfffa0000
	s_mov_b32 s99, -1
	v_lshl_add_u64 v[246:247], v[246:247], 0, s[98:99]
	global_load_dwordx4 v[112:115], v[246:247], off
	global_load_dwordx4 v[116:119], v[246:247], off offset:2048
	v_lshl_add_u64 v[248:249], v[248:249], 0, s[98:99]
	global_load_dwordx4 v[120:123], v[248:249], off
	global_load_dwordx4 v[124:127], v[248:249], off offset:2048
	v_lshl_add_u64 v[250:251], v[250:251], 0, s[98:99]
	global_load_dwordx4 v[128:131], v[250:251], off
	global_load_dwordx4 v[132:135], v[250:251], off offset:2048
	v_lshl_add_u64 v[252:253], v[252:253], 0, s[98:99]
	global_load_dwordx4 v[136:139], v[252:253], off
	global_load_dwordx4 v[140:143], v[252:253], off offset:2048
.LBB0_1790:
	s_sub_i32 s0, s55, 63
	s_lshl_b32 s56, s53, 15
	v_cmp_le_i32_e32 vcc, s0, v173
	s_and_saveexec_b64 s[44:45], vcc
	s_cbranch_execz .LBB0_1802
	s_sub_i32 s0, s55, 31
	v_add_u32_e32 v64, s56, v194
	v_cmp_le_i32_e32 vcc, s0, v173
	v_add_u32_e32 v186, v64, v205
	v_add_u32_e32 v185, v64, v206
	v_add_u32_e32 v184, v64, v207
	v_add_u32_e32 v183, v64, v208
	v_add_u32_e32 v182, v64, v209
	v_add_u32_e32 v181, v64, v210
	v_add_u32_e32 v180, v64, v211
	v_add_u32_e32 v175, v64, v212
	s_and_saveexec_b64 s[48:49], vcc
	s_cbranch_execz .Lattn_zero
	ds_read_b128 v[64:67], v186 offset:8192
	ds_read_b128 v[144:147], v185 offset:8192
	v_cmp_ge_i32_e32 vcc, s55, v230
	s_waitcnt lgkmcnt(1)
	v_mfma_f32_32x32x16_bf16 v[64:79], v[64:67], v[80:83], 0
	s_waitcnt lgkmcnt(0)
	v_mfma_f32_32x32x16_bf16 v[64:79], v[144:147], v[84:87], v[64:79]
	ds_read_b128 v[144:147], v184 offset:8192
	ds_read_b128 v[148:151], v183 offset:8192
	s_waitcnt lgkmcnt(1)
	v_mfma_f32_32x32x16_bf16 v[64:79], v[144:147], v[88:91], v[64:79]
	s_waitcnt lgkmcnt(0)
	v_mfma_f32_32x32x16_bf16 v[64:79], v[148:151], v[92:95], v[64:79]
	ds_read_b128 v[144:147], v182 offset:8192
	ds_read_b128 v[148:151], v181 offset:8192
	s_waitcnt lgkmcnt(1)
	v_mfma_f32_32x32x16_bf16 v[64:79], v[144:147], v[96:99], v[64:79]
	s_waitcnt lgkmcnt(0)
	v_mfma_f32_32x32x16_bf16 v[64:79], v[148:151], v[100:103], v[64:79]
	ds_read_b128 v[144:147], v180 offset:8192
	ds_read_b128 v[148:151], v175 offset:8192
	s_waitcnt lgkmcnt(1)
	v_mfma_f32_32x32x16_bf16 v[64:79], v[144:147], v[104:107], v[64:79]
	s_waitcnt lgkmcnt(0)
	v_mfma_f32_32x32x16_bf16 v[64:79], v[148:151], v[108:111], v[64:79]
	s_nop 11
	v_mul_f32_e32 v64, 0x3e0293ee, v64
	v_mul_f32_e32 v67, 0x3e0293ee, v67
	v_mul_f32_e32 v68, 0x3e0293ee, v68
	v_mul_f32_e32 v71, 0x3e0293ee, v71
	v_min_f32_e32 v64, 0x42700000, v64
	v_min_f32_e32 v67, 0x42700000, v67
	v_min_f32_e32 v68, 0x42700000, v68
	v_min_f32_e32 v144, 0x42700000, v71
	v_exp_f32_e32 v71, v64
	v_exp_f32_e32 v187, v67
	v_exp_f32_e32 v234, v68
	v_mul_f32_e32 v66, 0x3e0293ee, v66
	v_mul_f32_e32 v72, 0x3e0293ee, v72
	v_mul_f32_e32 v74, 0x3e0293ee, v74
	v_mul_f32_e32 v75, 0x3e0293ee, v75
	v_mul_f32_e32 v76, 0x3e0293ee, v76
	v_min_f32_e32 v66, 0x42700000, v66
	v_min_f32_e32 v72, 0x42700000, v72
	v_mul_f32_e32 v70, 0x3e0293ee, v70
	v_mul_f32_e32 v73, 0x3e0293ee, v73
	v_mul_f32_e32 v77, 0x3e0293ee, v77
	v_min_f32_e32 v74, 0x42700000, v74
	v_min_f32_e32 v75, 0x42700000, v75
	v_min_f32_e32 v76, 0x42700000, v76
	v_exp_f32_e32 v178, v66
	v_exp_f32_e32 v235, v72
	v_add_f32_e32 v66, 1.0, v71
	v_add_f32_e32 v72, 1.0, v187
	v_mul_f32_e32 v65, 0x3e0293ee, v65
	v_min_f32_e32 v70, 0x42700000, v70
	v_min_f32_e32 v145, 0x42700000, v73
	v_min_f32_e32 v77, 0x42700000, v77
	v_exp_f32_e32 v231, v144
	v_exp_f32_e32 v64, v74
	v_exp_f32_e32 v232, v75
	v_exp_f32_e32 v237, v76
	v_add_f32_e32 v75, 1.0, v234
	v_rcp_f32_e32 v74, v66
	v_rcp_f32_e32 v66, v72
	v_mul_f32_e32 v72, 0x3e0293ee, v78
	v_mul_f32_e32 v69, 0x3e0293ee, v69
	v_min_f32_e32 v65, 0x42700000, v65
	v_exp_f32_e32 v70, v70
	v_exp_f32_e32 v67, v145
	v_exp_f32_e32 v236, v77
	v_rcp_f32_e32 v77, v75
	v_min_f32_e32 v72, 0x42700000, v72
	v_mul_f32_e32 v75, 0x3e0293ee, v79
	v_min_f32_e32 v69, 0x42700000, v69
	v_exp_f32_e32 v65, v65
	v_exp_f32_e32 v72, v72
	v_min_f32_e32 v75, 0x42700000, v75
	v_exp_f32_e32 v73, v69
	v_add_f32_e32 v69, 1.0, v178
	v_exp_f32_e32 v78, v75
	v_add_f32_e32 v147, 1.0, v231
	v_rcp_f32_e32 v144, v69
	v_add_f32_e32 v69, 1.0, v237
	v_add_f32_e32 v146, 1.0, v70
	v_add_f32_e32 v148, 1.0, v235
	v_add_f32_e32 v149, 1.0, v67
	v_rcp_f32_e32 v233, v147
	v_rcp_f32_e32 v147, v69
	v_add_f32_e32 v69, 1.0, v236
	v_add_f32_e32 v68, 1.0, v65
	v_add_f32_e32 v151, 1.0, v232
	v_rcp_f32_e32 v238, v146
	v_rcp_f32_e32 v146, v148
	v_rcp_f32_e32 v148, v149
	v_rcp_f32_e32 v149, v69
	v_add_f32_e32 v69, 1.0, v72
	v_add_f32_e32 v145, 1.0, v73
	v_add_f32_e32 v150, 1.0, v64
	v_rcp_f32_e32 v76, v68
	v_rcp_f32_e32 v68, v151
	v_rcp_f32_e32 v151, v69
	v_add_f32_e32 v69, 1.0, v78
	v_rcp_f32_e32 v145, v145
	v_rcp_f32_e32 v150, v150
	v_rcp_f32_e32 v69, v69
	s_and_saveexec_b64 s[50:51], vcc
	s_cbranch_execz .LBB0_1796
; __device__ __forceinline__ int crow(int r, int hi) { return (r & 3) + 8 * (r >> 2) + 4 * hi; }
; __device__ __forceinline__ void sb_half(f32x16& pz, float& run, bool need_mask, int kb, int t, int hi) {
;     ...
;   if (need_mask) {
; #pragma unroll
;     for (int r = 0; r < 16; ++r) { if (kb + crow(r, hi) >= t) { l[r] = 1.f; pz[r] = 0.f; } }
;   }
	v_add_u32_e32 v75, s55, v195
	v_subrev_u32_e32 v79, 31, v75
	v_cmp_lt_i32_e32 vcc, v79, v174
	v_subrev_u32_e32 v79, 30, v75
	v_cmp_lt_i32_e64 s[0:1], v79, v174
	v_subrev_u32_e32 v79, 29, v75
	v_cmp_lt_i32_e64 s[6:7], v79, v174
	v_subrev_u32_e32 v79, 28, v75
	v_cmp_lt_i32_e64 s[8:9], v79, v174
	v_subrev_u32_e32 v79, 23, v75
	v_cmp_lt_i32_e64 s[10:11], v79, v174
	v_subrev_u32_e32 v79, 22, v75
	v_cmp_lt_i32_e64 s[12:13], v79, v174
	v_subrev_u32_e32 v79, 21, v75
	v_cmp_lt_i32_e64 s[14:15], v79, v174
	v_subrev_u32_e32 v79, 20, v75
	v_cmp_lt_i32_e64 s[16:17], v79, v174
	v_add_u32_e32 v79, -15, v75
	v_cmp_lt_i32_e64 s[18:19], v79, v174
	v_add_u32_e32 v79, -14, v75
	v_cmp_lt_i32_e64 s[20:21], v79, v174
	v_add_u32_e32 v79, -13, v75
	v_cmp_lt_i32_e64 s[22:23], v79, v174
	v_add_u32_e32 v79, -12, v75
	v_cmp_lt_i32_e64 s[24:25], v79, v174
	v_add_u32_e32 v79, -7, v75
	v_cmp_lt_i32_e64 s[26:27], v79, v174
	v_add_u32_e32 v79, -6, v75
	v_cmp_lt_i32_e64 s[28:29], v79, v174
	v_add_u32_e32 v79, -5, v75
	v_cmp_lt_i32_e64 s[30:31], v79, v174
	s_or_b64 s[28:29], s[30:31], s[28:29]
	s_or_b64 s[26:27], s[28:29], s[26:27]
	s_or_b64 s[24:25], s[26:27], s[24:25]
	s_or_b64 s[22:23], s[24:25], s[22:23]
	s_or_b64 s[20:21], s[22:23], s[20:21]
	s_or_b64 s[18:19], s[20:21], s[18:19]
	s_or_b64 s[16:17], s[18:19], s[16:17]
	s_or_b64 s[14:15], s[16:17], s[14:15]
	s_or_b64 s[12:13], s[14:15], s[12:13]
	s_or_b64 s[10:11], s[12:13], s[10:11]
	s_or_b64 s[8:9], s[10:11], s[8:9]
	s_or_b64 s[6:7], s[8:9], s[6:7]
	s_or_b64 s[0:1], s[6:7], s[0:1]
	s_or_b64 vcc, s[0:1], vcc
	v_add_u32_e32 v75, -4, v75
	v_cndmask_b32_e64 v72, 0, v72, s[30:31]
	v_cndmask_b32_e64 v236, 0, v236, s[28:29]
	v_cndmask_b32_e64 v237, 0, v237, s[26:27]
	v_cndmask_b32_e64 v232, 0, v232, s[24:25]
	v_cndmask_b32_e64 v64, 0, v64, s[22:23]
	v_cndmask_b32_e64 v67, 0, v67, s[20:21]
	v_cndmask_b32_e64 v235, 0, v235, s[18:19]
	v_cndmask_b32_e64 v231, 0, v231, s[16:17]
	v_cndmask_b32_e64 v70, 0, v70, s[14:15]
	v_cndmask_b32_e64 v73, 0, v73, s[12:13]
	v_cndmask_b32_e64 v234, 0, v234, s[10:11]
	v_cndmask_b32_e64 v187, 0, v187, s[8:9]
	v_cndmask_b32_e64 v178, 0, v178, s[6:7]
	v_cndmask_b32_e64 v65, 0, v65, s[0:1]
	v_cndmask_b32_e32 v71, 0, v71, vcc
	v_cndmask_b32_e64 v149, 1.0, v149, s[28:29]
	v_cndmask_b32_e64 v147, 1.0, v147, s[26:27]
	v_cndmask_b32_e64 v68, 1.0, v68, s[24:25]
	v_cndmask_b32_e64 v150, 1.0, v150, s[22:23]
	v_cndmask_b32_e64 v148, 1.0, v148, s[20:21]
	v_cndmask_b32_e64 v146, 1.0, v146, s[18:19]
	v_cndmask_b32_e64 v233, 1.0, v233, s[16:17]
	v_cndmask_b32_e64 v238, 1.0, v238, s[14:15]
	v_cndmask_b32_e64 v145, 1.0, v145, s[12:13]
	v_cndmask_b32_e64 v77, 1.0, v77, s[10:11]
	v_cndmask_b32_e64 v66, 1.0, v66, s[8:9]
	v_cndmask_b32_e64 v144, 1.0, v144, s[6:7]
	v_cndmask_b32_e64 v76, 1.0, v76, s[0:1]
	v_cndmask_b32_e32 v74, 1.0, v74, vcc
	v_cndmask_b32_e64 v151, 1.0, v151, s[30:31]
	v_cmp_ge_i32_e32 vcc, v75, v174
	s_and_saveexec_b64 s[0:1], vcc
	v_mov_b32_e32 v78, 0
	v_mov_b32_e32 v69, 1.0
	s_or_b64 exec, exec, s[0:1]

; #define SLOAD(KT) do { _Pragma("unroll") for (int ii = 0; ii < 4; ++ii) { const u16* kp = kbase + (size_t)((KT) * 64 + sr + 16 * ii) * 3072; \
;       stk[ii] = *(const u32x4*)kp; stv[ii] = *(const u32x4*)(kp + 1024); } } while (0)
; __device__ __forceinline__ void attn_phase(const Params& p, char* smem, int bid, int nblk) {
;     ...
;       if (kt > 0) SLOAD(kt - 1);
	.amdhsa_kernel _Z4mega6Params
		.amdhsa_group_segment_fixed_size 73744
		.amdhsa_private_segment_fixed_size 0
		.amdhsa_kernarg_size 496
		.amdhsa_user_sgpr_count 2
		.amdhsa_user_sgpr_dispatch_ptr 0
		.amdhsa_user_sgpr_queue_ptr 0
		.amdhsa_user_sgpr_kernarg_segment_ptr 1
		.amdhsa_user_sgpr_dispatch_id 0
		.amdhsa_user_sgpr_kernarg_preload_length 0
		.amdhsa_user_sgpr_kernarg_preload_offset 0
		.amdhsa_user_sgpr_private_segment_size 0
		.amdhsa_uses_dynamic_stack 0
		.amdhsa_enable_private_segment 0
		.amdhsa_system_sgpr_workgroup_id_x 1
		.amdhsa_system_sgpr_workgroup_id_y 0
		.amdhsa_system_sgpr_workgroup_id_z 0
		.amdhsa_system_sgpr_workgroup_info 0
		.amdhsa_system_vgpr_workitem_id 2
		.amdhsa_next_free_vgpr 256
		.amdhsa_next_free_sgpr 102
		.amdhsa_accum_offset 256
		.amdhsa_reserve_vcc 1
		.amdhsa_float_round_mode_32 0
		.amdhsa_float_round_mode_16_64 0
		.amdhsa_float_denorm_mode_32 3
		.amdhsa_float_denorm_mode_16_64 3
		.amdhsa_dx10_clamp 1
		.amdhsa_ieee_mode 1
		.amdhsa_fp16_overflow 0
		.amdhsa_tg_split 0
		.amdhsa_exception_fp_ieee_invalid_op 0
		.amdhsa_exception_fp_denorm_src 0
		.amdhsa_exception_fp_ieee_div_zero 0
		.amdhsa_exception_fp_ieee_overflow 0
		.amdhsa_exception_fp_ieee_underflow 0
		.amdhsa_exception_fp_ieee_inexact 0
		.amdhsa_exception_int_div_zero 0
	.end_amdhsa_kernel

; #define SLOAD(KT) do { _Pragma("unroll") for (int ii = 0; ii < 4; ++ii) { const u16* kp = kbase + (size_t)((KT) * 64 + sr + 16 * ii) * 3072; \
;       stk[ii] = *(const u32x4*)kp; stv[ii] = *(const u32x4*)(kp + 1024); } } while (0)
; __device__ __forceinline__ void attn_phase(const Params& p, char* smem, int bid, int nblk) {
;     ...
;       if (kt > 0) SLOAD(kt - 1);
amdhsa.kernels:
  - .agpr_count:     0
    .args:
      - .offset:         0
        .size:           240
        .value_kind:     by_value
      - .offset:         240
        .size:           4
        .value_kind:     hidden_block_count_x
      - .offset:         244
        .size:           4
        .value_kind:     hidden_block_count_y
      - .offset:         248
        .size:           4
        .value_kind:     hidden_block_count_z
      - .offset:         252
        .size:           2
        .value_kind:     hidden_group_size_x
      - .offset:         254
        .size:           2
        .value_kind:     hidden_group_size_y
      - .offset:         256
        .size:           2
        .value_kind:     hidden_group_size_z
      - .offset:         258
        .size:           2
        .value_kind:     hidden_remainder_x
      - .offset:         260
        .size:           2
        .value_kind:     hidden_remainder_y
      - .offset:         262
        .size:           2
        .value_kind:     hidden_remainder_z
      - .offset:         280
        .size:           8
        .value_kind:     hidden_global_offset_x
      - .offset:         288
        .size:           8
        .value_kind:     hidden_global_offset_y
      - .offset:         296
        .size:           8
        .value_kind:     hidden_global_offset_z
      - .offset:         304
        .size:           2
        .value_kind:     hidden_grid_dims
      - .offset:         328
        .size:           8
        .value_kind:     hidden_multigrid_sync_arg
    .group_segment_fixed_size: 73744
    .kernarg_segment_align: 8
    .kernarg_segment_size: 496
    .language:       OpenCL C
    .language_version:
      - 2
      - 0
    .max_flat_workgroup_size: 256
    .name:           _Z4mega6Params
    .private_segment_fixed_size: 0
    .sgpr_count:     108
    .sgpr_spill_count: 91
    .symbol:         _Z4mega6Params.kd
    .uniform_work_group_size: 1
    .uses_dynamic_stack: false
    .vgpr_count:     256
    .vgpr_spill_count: 0
    .wavefront_size: 64
